# v11 plus GEMM K-loop load segments reordered: LDS-DMA stages issued before the ds_read fragment reads
# baseline (speedup 1.0000x reference)
.LBB0_278:
	s_add_u32 s8, s6, 0xfff80080
	s_addc_u32 s9, s7, -1
	s_add_i32 s73, 0, 0x10000
	s_cmp_eq_u32 s72, 28
	s_cselect_b32 s39, s43, s9
	s_cselect_b32 s38, s52, s8
	s_cselect_b32 s9, s45, s67
	s_cselect_b32 s8, s65, s66
	s_add_i32 s76, 0, 0x14000
	v_lshl_add_u64 v[188:189], s[6:7], 0, v[174:175]
	s_add_i32 m0, s47, 0xc000
	s_nop 0
	global_load_lds_dwordx4 v[188:189], off
	v_lshl_add_u64 v[188:189], s[6:7], 0, v[172:173]
	s_add_i32 m0, s47, 0xe000
	s_nop 0
	global_load_lds_dwordx4 v[188:189], off
	v_add_u32_e32 v2, s73, v191
	ds_read_b128 v[132:135], v2
	ds_read_b128 v[136:139], v2 offset:1024
	ds_read_b128 v[140:143], v2 offset:2048
	ds_read_b128 v[144:147], v2 offset:3072
	v_add_u32_e32 v2, s76, v191
	ds_read_b128 v[148:151], v2
	ds_read_b128 v[152:155], v2 offset:1024
	ds_read_b128 v[156:159], v2 offset:2048
	ds_read_b128 v[160:163], v2 offset:3072
	ds_read_b128 v[176:179], v197
	ds_read_b128 v[180:183], v197 offset:1024
	ds_read_b128 v[184:187], v197 offset:2048
	ds_read_b128 v[192:195], v197 offset:3072
	ds_read_b128 v[198:201], v197 offset:4096
	ds_read_b128 v[202:205], v197 offset:5120
	ds_read_b128 v[206:209], v197 offset:6144
	ds_read_b128 v[220:223], v197 offset:7168
	s_waitcnt vmcnt(8)
	s_waitcnt lgkmcnt(0)
	s_barrier
	s_setprio 1
	s_waitcnt lgkmcnt(0)
	v_mfma_f32_16x16x32_bf16 v[124:127], v[132:135], v[176:179], v[124:127]
	v_mfma_f32_16x16x32_bf16 v[128:131], v[140:143], v[176:179], v[128:131]
	v_mfma_f32_16x16x32_bf16 v[108:111], v[132:135], v[184:187], v[108:111]
	v_mfma_f32_16x16x32_bf16 v[112:115], v[140:143], v[184:187], v[112:115]
	v_mfma_f32_16x16x32_bf16 v[92:95], v[132:135], v[198:201], v[92:95]
	v_mfma_f32_16x16x32_bf16 v[96:99], v[140:143], v[198:201], v[96:99]
	v_mfma_f32_16x16x32_bf16 v[76:79], v[132:135], v[206:209], v[76:79]
	v_mfma_f32_16x16x32_bf16 v[80:83], v[140:143], v[206:209], v[80:83]
	v_mfma_f32_16x16x32_bf16 v[124:127], v[136:139], v[180:183], v[124:127]
	v_mfma_f32_16x16x32_bf16 v[128:131], v[144:147], v[180:183], v[128:131]
	v_mfma_f32_16x16x32_bf16 v[108:111], v[136:139], v[192:195], v[108:111]
	v_mfma_f32_16x16x32_bf16 v[112:115], v[144:147], v[192:195], v[112:115]
	v_mfma_f32_16x16x32_bf16 v[92:95], v[136:139], v[202:205], v[92:95]
	v_mfma_f32_16x16x32_bf16 v[96:99], v[144:147], v[202:205], v[96:99]
	v_mfma_f32_16x16x32_bf16 v[76:79], v[136:139], v[220:223], v[76:79]
	v_mfma_f32_16x16x32_bf16 v[80:83], v[144:147], v[220:223], v[80:83]
	s_setprio 0
	s_setprio 1
	v_mfma_f32_16x16x32_bf16 v[116:119], v[148:151], v[176:179], v[116:119]
	v_mfma_f32_16x16x32_bf16 v[120:123], v[156:159], v[176:179], v[120:123]
	v_mfma_f32_16x16x32_bf16 v[100:103], v[148:151], v[184:187], v[100:103]
	v_mfma_f32_16x16x32_bf16 v[104:107], v[156:159], v[184:187], v[104:107]
	v_mfma_f32_16x16x32_bf16 v[84:87], v[148:151], v[198:201], v[84:87]
	v_mfma_f32_16x16x32_bf16 v[88:91], v[156:159], v[198:201], v[88:91]
	v_mfma_f32_16x16x32_bf16 v[68:71], v[148:151], v[206:209], v[68:71]
	v_mfma_f32_16x16x32_bf16 v[72:75], v[156:159], v[206:209], v[72:75]
	v_mfma_f32_16x16x32_bf16 v[116:119], v[152:155], v[180:183], v[116:119]
	v_mfma_f32_16x16x32_bf16 v[120:123], v[160:163], v[180:183], v[120:123]
	v_mfma_f32_16x16x32_bf16 v[100:103], v[152:155], v[192:195], v[100:103]
	v_mfma_f32_16x16x32_bf16 v[104:107], v[160:163], v[192:195], v[104:107]
	v_mfma_f32_16x16x32_bf16 v[84:87], v[152:155], v[202:205], v[84:87]
	v_mfma_f32_16x16x32_bf16 v[88:91], v[160:163], v[202:205], v[88:91]
	v_mfma_f32_16x16x32_bf16 v[68:71], v[152:155], v[220:223], v[68:71]
	v_mfma_f32_16x16x32_bf16 v[72:75], v[160:163], v[220:223], v[72:75]
	s_setprio 0
	s_barrier
	s_add_i32 s73, s73, s46
	v_lshl_add_u64 v[188:189], s[8:9], 0, v[168:169]
	s_mov_b32 m0, s73
	s_nop 0
	global_load_lds_dwordx4 v[188:189], off
	s_add_i32 m0, s73, 0x2000
	s_add_u32 s74, s8, 0x80000
	v_lshl_add_u64 v[210:211], s[8:9], 0, v[164:165]
	s_addc_u32 s75, s9, 0
	s_add_i32 s73, s76, s46
	global_load_lds_dwordx4 v[210:211], off
	v_lshl_add_u64 v[216:217], s[74:75], 0, v[168:169]
	s_mov_b32 m0, s73
	v_lshl_add_u64 v[224:225], s[38:39], 0, v[166:167]
	global_load_lds_dwordx4 v[216:217], off
	v_lshl_add_u64 v[216:217], s[74:75], 0, v[164:165]
	s_add_i32 m0, s73, 0x2000
	s_mov_b64 s[76:77], 0x80
	global_load_lds_dwordx4 v[216:217], off
	v_lshl_add_u64 v[216:217], s[38:39], 0, v[170:171]
	s_mov_b32 m0, s47
	s_nop 0
	global_load_lds_dwordx4 v[216:217], off
	s_mov_b32 m0, s48
	s_nop 0
	global_load_lds_dwordx4 v[224:225], off
	ds_read_b128 v[176:179], v197 offset:16384
	ds_read_b128 v[180:183], v197 offset:17408
	ds_read_b128 v[184:187], v197 offset:18432
	ds_read_b128 v[192:195], v197 offset:19456
	ds_read_b128 v[198:201], v197 offset:20480
	ds_read_b128 v[202:205], v197 offset:21504
	ds_read_b128 v[206:209], v197 offset:22528
	ds_read_b128 v[220:223], v197 offset:23552
	s_waitcnt vmcnt(8)
	s_waitcnt lgkmcnt(0)
	s_barrier
	s_setprio 1
	s_waitcnt lgkmcnt(0)
	v_mfma_f32_16x16x32_bf16 v[60:63], v[132:135], v[176:179], v[60:63]
	v_mfma_f32_16x16x32_bf16 v[64:67], v[140:143], v[176:179], v[64:67]
	v_mfma_f32_16x16x32_bf16 v[44:47], v[132:135], v[184:187], v[44:47]
	v_mfma_f32_16x16x32_bf16 v[48:51], v[140:143], v[184:187], v[48:51]
	v_mfma_f32_16x16x32_bf16 v[28:31], v[132:135], v[198:201], v[28:31]
	v_mfma_f32_16x16x32_bf16 v[32:35], v[140:143], v[198:201], v[32:35]
	v_mfma_f32_16x16x32_bf16 v[12:15], v[132:135], v[206:209], v[12:15]
	v_mfma_f32_16x16x32_bf16 v[16:19], v[140:143], v[206:209], v[16:19]
	v_mfma_f32_16x16x32_bf16 v[60:63], v[136:139], v[180:183], v[60:63]
	v_mfma_f32_16x16x32_bf16 v[64:67], v[144:147], v[180:183], v[64:67]
	v_mfma_f32_16x16x32_bf16 v[44:47], v[136:139], v[192:195], v[44:47]
	v_mfma_f32_16x16x32_bf16 v[48:51], v[144:147], v[192:195], v[48:51]
	v_mfma_f32_16x16x32_bf16 v[28:31], v[136:139], v[202:205], v[28:31]
	v_mfma_f32_16x16x32_bf16 v[32:35], v[144:147], v[202:205], v[32:35]
	v_mfma_f32_16x16x32_bf16 v[12:15], v[136:139], v[220:223], v[12:15]
	v_mfma_f32_16x16x32_bf16 v[16:19], v[144:147], v[220:223], v[16:19]
	s_setprio 0
	s_setprio 1
	v_mfma_f32_16x16x32_bf16 v[52:55], v[148:151], v[176:179], v[52:55]
	v_mfma_f32_16x16x32_bf16 v[56:59], v[156:159], v[176:179], v[56:59]
	v_mfma_f32_16x16x32_bf16 v[36:39], v[148:151], v[184:187], v[36:39]
	v_mfma_f32_16x16x32_bf16 v[40:43], v[156:159], v[184:187], v[40:43]
	v_mfma_f32_16x16x32_bf16 v[20:23], v[148:151], v[198:201], v[20:23]
	v_mfma_f32_16x16x32_bf16 v[24:27], v[156:159], v[198:201], v[24:27]
	v_mfma_f32_16x16x32_bf16 v[4:7], v[148:151], v[206:209], v[4:7]
	v_mfma_f32_16x16x32_bf16 v[8:11], v[156:159], v[206:209], v[8:11]
	v_mfma_f32_16x16x32_bf16 v[52:55], v[152:155], v[180:183], v[52:55]
	v_mfma_f32_16x16x32_bf16 v[56:59], v[160:163], v[180:183], v[56:59]
	v_mfma_f32_16x16x32_bf16 v[36:39], v[152:155], v[192:195], v[36:39]
	v_mfma_f32_16x16x32_bf16 v[40:43], v[160:163], v[192:195], v[40:43]
	v_mfma_f32_16x16x32_bf16 v[20:23], v[152:155], v[202:205], v[20:23]
	v_mfma_f32_16x16x32_bf16 v[24:27], v[160:163], v[202:205], v[24:27]
	v_mfma_f32_16x16x32_bf16 v[4:7], v[152:155], v[220:223], v[4:7]
	v_mfma_f32_16x16x32_bf16 v[8:11], v[160:163], v[220:223], v[8:11]
	s_setprio 0
	s_barrier
	s_add_i32 s73, 0, 0x18000
	s_add_i32 s74, 0, 0x1c000
	s_add_u32 s38, s38, 0x80000
	s_addc_u32 s39, s39, 0
	s_mov_b32 m0, s49
	v_lshl_add_u64 v[226:227], s[38:39], 0, v[170:171]
	global_load_lds_dwordx4 v[226:227], off
	v_lshl_add_u64 v[226:227], s[38:39], 0, v[166:167]
	s_mov_b32 m0, s54
	s_nop 0
	global_load_lds_dwordx4 v[226:227], off
	v_add_u32_e32 v2, s73, v191
	ds_read_b128 v[132:135], v2
	ds_read_b128 v[136:139], v2 offset:1024
	ds_read_b128 v[140:143], v2 offset:2048
	ds_read_b128 v[144:147], v2 offset:3072
	v_add_u32_e32 v2, s74, v191
	ds_read_b128 v[148:151], v2
	ds_read_b128 v[152:155], v2 offset:1024
	ds_read_b128 v[156:159], v2 offset:2048
	ds_read_b128 v[160:163], v2 offset:3072
	ds_read_b128 v[176:179], v197 offset:32768
	ds_read_b128 v[180:183], v197 offset:33792
	ds_read_b128 v[184:187], v197 offset:34816
	ds_read_b128 v[192:195], v197 offset:35840
	ds_read_b128 v[198:201], v197 offset:36864
	ds_read_b128 v[202:205], v197 offset:37888
	ds_read_b128 v[206:209], v197 offset:38912
	ds_read_b128 v[220:223], v197 offset:39936
	s_waitcnt vmcnt(8)
	s_waitcnt lgkmcnt(0)
	s_barrier
	s_setprio 1
	s_waitcnt lgkmcnt(0)
	v_mfma_f32_16x16x32_bf16 v[124:127], v[132:135], v[176:179], v[124:127]
	v_mfma_f32_16x16x32_bf16 v[128:131], v[140:143], v[176:179], v[128:131]
	v_mfma_f32_16x16x32_bf16 v[108:111], v[132:135], v[184:187], v[108:111]
	v_mfma_f32_16x16x32_bf16 v[112:115], v[140:143], v[184:187], v[112:115]
	v_mfma_f32_16x16x32_bf16 v[92:95], v[132:135], v[198:201], v[92:95]
	v_mfma_f32_16x16x32_bf16 v[96:99], v[140:143], v[198:201], v[96:99]
	v_mfma_f32_16x16x32_bf16 v[76:79], v[132:135], v[206:209], v[76:79]
	v_mfma_f32_16x16x32_bf16 v[80:83], v[140:143], v[206:209], v[80:83]
	v_mfma_f32_16x16x32_bf16 v[124:127], v[136:139], v[180:183], v[124:127]
	v_mfma_f32_16x16x32_bf16 v[128:131], v[144:147], v[180:183], v[128:131]
	v_mfma_f32_16x16x32_bf16 v[108:111], v[136:139], v[192:195], v[108:111]
	v_mfma_f32_16x16x32_bf16 v[112:115], v[144:147], v[192:195], v[112:115]
	v_mfma_f32_16x16x32_bf16 v[92:95], v[136:139], v[202:205], v[92:95]
	v_mfma_f32_16x16x32_bf16 v[96:99], v[144:147], v[202:205], v[96:99]
	v_mfma_f32_16x16x32_bf16 v[76:79], v[136:139], v[220:223], v[76:79]
	v_mfma_f32_16x16x32_bf16 v[80:83], v[144:147], v[220:223], v[80:83]
	s_setprio 0
	s_setprio 1
	v_mfma_f32_16x16x32_bf16 v[116:119], v[148:151], v[176:179], v[116:119]
	v_mfma_f32_16x16x32_bf16 v[120:123], v[156:159], v[176:179], v[120:123]
	v_mfma_f32_16x16x32_bf16 v[100:103], v[148:151], v[184:187], v[100:103]
	v_mfma_f32_16x16x32_bf16 v[104:107], v[156:159], v[184:187], v[104:107]
	v_mfma_f32_16x16x32_bf16 v[84:87], v[148:151], v[198:201], v[84:87]
	v_mfma_f32_16x16x32_bf16 v[88:91], v[156:159], v[198:201], v[88:91]
	v_mfma_f32_16x16x32_bf16 v[68:71], v[148:151], v[206:209], v[68:71]
	v_mfma_f32_16x16x32_bf16 v[72:75], v[156:159], v[206:209], v[72:75]
	v_mfma_f32_16x16x32_bf16 v[116:119], v[152:155], v[180:183], v[116:119]
	v_mfma_f32_16x16x32_bf16 v[120:123], v[160:163], v[180:183], v[120:123]
	v_mfma_f32_16x16x32_bf16 v[100:103], v[152:155], v[192:195], v[100:103]
	v_mfma_f32_16x16x32_bf16 v[104:107], v[160:163], v[192:195], v[104:107]
	v_mfma_f32_16x16x32_bf16 v[84:87], v[152:155], v[202:205], v[84:87]
	v_mfma_f32_16x16x32_bf16 v[88:91], v[160:163], v[202:205], v[88:91]
	v_mfma_f32_16x16x32_bf16 v[68:71], v[152:155], v[220:223], v[68:71]
	v_mfma_f32_16x16x32_bf16 v[72:75], v[160:163], v[220:223], v[72:75]
	s_setprio 0
	s_barrier
	s_add_i32 s38, s73, s46
	v_lshl_add_u64 v[188:189], v[188:189], 0, s[76:77]
	s_mov_b32 m0, s38
	s_nop 0
	global_load_lds_dwordx4 v[188:189], off
	s_add_i32 m0, s38, 0x2000
	s_add_u32 s8, s8, 0x80080
	v_lshl_add_u64 v[188:189], v[210:211], 0, s[76:77]
	s_addc_u32 s9, s9, 0
	s_add_i32 s38, s74, s46
	global_load_lds_dwordx4 v[188:189], off
	v_lshl_add_u64 v[188:189], s[8:9], 0, v[168:169]
	s_mov_b32 m0, s38
	s_nop 0
	global_load_lds_dwordx4 v[188:189], off
	v_lshl_add_u64 v[188:189], s[8:9], 0, v[164:165]
	s_add_i32 m0, s38, 0x2000
	s_nop 0
	global_load_lds_dwordx4 v[188:189], off
	v_lshl_add_u64 v[188:189], v[216:217], 0, s[76:77]
	s_mov_b32 m0, s59
	s_nop 0
	global_load_lds_dwordx4 v[188:189], off
	v_lshl_add_u64 v[188:189], v[224:225], 0, s[76:77]
	s_mov_b32 m0, s60
	s_nop 0
	global_load_lds_dwordx4 v[188:189], off
	ds_read_b128 v[176:179], v197 offset:49152
	ds_read_b128 v[180:183], v197 offset:50176
	ds_read_b128 v[184:187], v197 offset:51200
	ds_read_b128 v[192:195], v197 offset:52224
	ds_read_b128 v[198:201], v197 offset:53248
	ds_read_b128 v[202:205], v197 offset:54272
	ds_read_b128 v[206:209], v197 offset:55296
	ds_read_b128 v[220:223], v197 offset:56320
	s_waitcnt vmcnt(8)
	s_waitcnt lgkmcnt(0)
	s_barrier
	s_setprio 1
	s_waitcnt lgkmcnt(0)
	v_mfma_f32_16x16x32_bf16 v[60:63], v[132:135], v[176:179], v[60:63]
	v_mfma_f32_16x16x32_bf16 v[64:67], v[140:143], v[176:179], v[64:67]
	v_mfma_f32_16x16x32_bf16 v[44:47], v[132:135], v[184:187], v[44:47]
	v_mfma_f32_16x16x32_bf16 v[48:51], v[140:143], v[184:187], v[48:51]
	v_mfma_f32_16x16x32_bf16 v[28:31], v[132:135], v[198:201], v[28:31]
	v_mfma_f32_16x16x32_bf16 v[32:35], v[140:143], v[198:201], v[32:35]
	v_mfma_f32_16x16x32_bf16 v[12:15], v[132:135], v[206:209], v[12:15]
	v_mfma_f32_16x16x32_bf16 v[16:19], v[140:143], v[206:209], v[16:19]
	v_mfma_f32_16x16x32_bf16 v[60:63], v[136:139], v[180:183], v[60:63]
	v_mfma_f32_16x16x32_bf16 v[64:67], v[144:147], v[180:183], v[64:67]
	v_mfma_f32_16x16x32_bf16 v[44:47], v[136:139], v[192:195], v[44:47]
	v_mfma_f32_16x16x32_bf16 v[48:51], v[144:147], v[192:195], v[48:51]
	v_mfma_f32_16x16x32_bf16 v[28:31], v[136:139], v[202:205], v[28:31]
	v_mfma_f32_16x16x32_bf16 v[32:35], v[144:147], v[202:205], v[32:35]
	v_mfma_f32_16x16x32_bf16 v[12:15], v[136:139], v[220:223], v[12:15]
	v_mfma_f32_16x16x32_bf16 v[16:19], v[144:147], v[220:223], v[16:19]
	s_setprio 0
	s_setprio 1
	v_mfma_f32_16x16x32_bf16 v[52:55], v[148:151], v[176:179], v[52:55]
	v_mfma_f32_16x16x32_bf16 v[56:59], v[156:159], v[176:179], v[56:59]
	v_mfma_f32_16x16x32_bf16 v[36:39], v[148:151], v[184:187], v[36:39]
	v_mfma_f32_16x16x32_bf16 v[40:43], v[156:159], v[184:187], v[40:43]
	v_mfma_f32_16x16x32_bf16 v[20:23], v[148:151], v[198:201], v[20:23]
	v_mfma_f32_16x16x32_bf16 v[24:27], v[156:159], v[198:201], v[24:27]
	v_mfma_f32_16x16x32_bf16 v[4:7], v[148:151], v[206:209], v[4:7]
	v_mfma_f32_16x16x32_bf16 v[8:11], v[156:159], v[206:209], v[8:11]
	v_mfma_f32_16x16x32_bf16 v[52:55], v[152:155], v[180:183], v[52:55]
	v_mfma_f32_16x16x32_bf16 v[56:59], v[160:163], v[180:183], v[56:59]
	v_mfma_f32_16x16x32_bf16 v[36:39], v[152:155], v[192:195], v[36:39]
	v_mfma_f32_16x16x32_bf16 v[40:43], v[160:163], v[192:195], v[40:43]
	v_mfma_f32_16x16x32_bf16 v[20:23], v[152:155], v[202:205], v[20:23]
	v_mfma_f32_16x16x32_bf16 v[24:27], v[160:163], v[202:205], v[24:27]
	v_mfma_f32_16x16x32_bf16 v[4:7], v[152:155], v[220:223], v[4:7]
	v_mfma_f32_16x16x32_bf16 v[8:11], v[160:163], v[220:223], v[8:11]
	s_setprio 0
	s_barrier
	s_add_i32 s72, s72, 2
	s_add_u32 s66, s66, 0x100
	s_addc_u32 s67, s67, 0
	s_add_u32 s6, s6, 0x100
	s_addc_u32 s7, s7, 0
	s_cmp_gt_u32 s72, 29
	s_cbranch_scc0 .LBB0_278
	s_and_b64 vcc, exec, s[18:19]
	s_cbranch_vccz .LBB0_281
	s_barrier

.LBB0_1229:
	s_add_u32 s20, s18, 0xfff80080
	s_addc_u32 s21, s19, -1
	s_add_i32 s56, 0, 0x10000
	s_cmp_eq_u32 s52, 28
	s_cselect_b32 s23, s13, s21
	s_cselect_b32 s22, s46, s20
	s_cselect_b32 s21, s11, s49
	s_cselect_b32 s20, s47, s48
	s_add_i32 s58, 0, 0x14000
	v_lshl_add_u64 v[208:209], s[18:19], 0, v[198:199]
	s_add_i32 m0, s29, 0xc000
	s_nop 0
	global_load_lds_dwordx4 v[208:209], off
	v_lshl_add_u64 v[208:209], s[18:19], 0, v[196:197]
	s_add_i32 m0, s29, 0xe000
	s_nop 0
	global_load_lds_dwordx4 v[208:209], off
	v_add_u32_e32 v2, s56, v216
	ds_read_b128 v[132:135], v2
	ds_read_b128 v[136:139], v2 offset:1024
	ds_read_b128 v[140:143], v2 offset:2048
	ds_read_b128 v[144:147], v2 offset:3072
	v_add_u32_e32 v2, s58, v216
	ds_read_b128 v[148:151], v2
	ds_read_b128 v[152:155], v2 offset:1024
	ds_read_b128 v[156:159], v2 offset:2048
	ds_read_b128 v[160:163], v2 offset:3072
	ds_read_b128 v[164:167], v217
	ds_read_b128 v[168:171], v217 offset:1024
	ds_read_b128 v[172:175], v217 offset:2048
	ds_read_b128 v[176:179], v217 offset:3072
	ds_read_b128 v[180:183], v217 offset:4096
	ds_read_b128 v[184:187], v217 offset:5120
	ds_read_b128 v[200:203], v217 offset:6144
	ds_read_b128 v[204:207], v217 offset:7168
	s_waitcnt vmcnt(8)
	s_waitcnt lgkmcnt(0)
	s_barrier
	s_setprio 1
	s_waitcnt lgkmcnt(0)
	v_mfma_f32_16x16x32_bf16 v[128:131], v[132:135], v[164:167], v[128:131]
	v_mfma_f32_16x16x32_bf16 v[124:127], v[140:143], v[164:167], v[124:127]
	v_mfma_f32_16x16x32_bf16 v[112:115], v[132:135], v[172:175], v[112:115]
	v_mfma_f32_16x16x32_bf16 v[108:111], v[140:143], v[172:175], v[108:111]
	v_mfma_f32_16x16x32_bf16 v[96:99], v[132:135], v[180:183], v[96:99]
	v_mfma_f32_16x16x32_bf16 v[92:95], v[140:143], v[180:183], v[92:95]
	v_mfma_f32_16x16x32_bf16 v[80:83], v[132:135], v[200:203], v[80:83]
	v_mfma_f32_16x16x32_bf16 v[76:79], v[140:143], v[200:203], v[76:79]
	v_mfma_f32_16x16x32_bf16 v[128:131], v[136:139], v[168:171], v[128:131]
	v_mfma_f32_16x16x32_bf16 v[124:127], v[144:147], v[168:171], v[124:127]
	v_mfma_f32_16x16x32_bf16 v[112:115], v[136:139], v[176:179], v[112:115]
	v_mfma_f32_16x16x32_bf16 v[108:111], v[144:147], v[176:179], v[108:111]
	v_mfma_f32_16x16x32_bf16 v[96:99], v[136:139], v[184:187], v[96:99]
	v_mfma_f32_16x16x32_bf16 v[92:95], v[144:147], v[184:187], v[92:95]
	v_mfma_f32_16x16x32_bf16 v[80:83], v[136:139], v[204:207], v[80:83]
	v_mfma_f32_16x16x32_bf16 v[76:79], v[144:147], v[204:207], v[76:79]
	s_setprio 0
	s_setprio 1
	v_mfma_f32_16x16x32_bf16 v[120:123], v[148:151], v[164:167], v[120:123]
	v_mfma_f32_16x16x32_bf16 v[116:119], v[156:159], v[164:167], v[116:119]
	v_mfma_f32_16x16x32_bf16 v[104:107], v[148:151], v[172:175], v[104:107]
	v_mfma_f32_16x16x32_bf16 v[100:103], v[156:159], v[172:175], v[100:103]
	v_mfma_f32_16x16x32_bf16 v[88:91], v[148:151], v[180:183], v[88:91]
	v_mfma_f32_16x16x32_bf16 v[84:87], v[156:159], v[180:183], v[84:87]
	v_mfma_f32_16x16x32_bf16 v[72:75], v[148:151], v[200:203], v[72:75]
	v_mfma_f32_16x16x32_bf16 v[68:71], v[156:159], v[200:203], v[68:71]
	v_mfma_f32_16x16x32_bf16 v[120:123], v[152:155], v[168:171], v[120:123]
	v_mfma_f32_16x16x32_bf16 v[116:119], v[160:163], v[168:171], v[116:119]
	v_mfma_f32_16x16x32_bf16 v[104:107], v[152:155], v[176:179], v[104:107]
	v_mfma_f32_16x16x32_bf16 v[100:103], v[160:163], v[176:179], v[100:103]
	v_mfma_f32_16x16x32_bf16 v[88:91], v[152:155], v[184:187], v[88:91]
	v_mfma_f32_16x16x32_bf16 v[84:87], v[160:163], v[184:187], v[84:87]
	v_mfma_f32_16x16x32_bf16 v[72:75], v[152:155], v[204:207], v[72:75]
	v_mfma_f32_16x16x32_bf16 v[68:71], v[160:163], v[204:207], v[68:71]
	s_setprio 0
	s_barrier
	s_add_i32 s56, s56, s28
	v_lshl_add_u64 v[208:209], s[20:21], 0, v[192:193]
	s_mov_b32 m0, s56
	s_nop 0
	global_load_lds_dwordx4 v[208:209], off
	s_add_i32 m0, s56, 0x2000
	s_add_u32 s56, s20, 0x80000
	v_lshl_add_u64 v[210:211], s[20:21], 0, v[188:189]
	s_addc_u32 s57, s21, 0
	s_add_i32 s58, s58, s28
	global_load_lds_dwordx4 v[210:211], off
	v_lshl_add_u64 v[220:221], s[56:57], 0, v[192:193]
	s_mov_b32 m0, s58
	v_lshl_add_u64 v[222:223], s[22:23], 0, v[190:191]
	global_load_lds_dwordx4 v[220:221], off
	v_lshl_add_u64 v[220:221], s[56:57], 0, v[188:189]
	s_add_i32 m0, s58, 0x2000
	s_nop 0
	global_load_lds_dwordx4 v[220:221], off
	v_lshl_add_u64 v[220:221], s[22:23], 0, v[194:195]
	s_mov_b32 m0, s29
	s_nop 0
	global_load_lds_dwordx4 v[220:221], off
	s_mov_b32 m0, s30
	s_nop 0
	global_load_lds_dwordx4 v[222:223], off
	ds_read_b128 v[164:167], v217 offset:16384
	ds_read_b128 v[168:171], v217 offset:17408
	ds_read_b128 v[172:175], v217 offset:18432
	ds_read_b128 v[176:179], v217 offset:19456
	ds_read_b128 v[180:183], v217 offset:20480
	ds_read_b128 v[184:187], v217 offset:21504
	ds_read_b128 v[200:203], v217 offset:22528
	ds_read_b128 v[204:207], v217 offset:23552
	s_waitcnt vmcnt(8)
	s_waitcnt lgkmcnt(0)
	s_barrier
	s_setprio 1
	s_waitcnt lgkmcnt(0)
	v_mfma_f32_16x16x32_bf16 v[64:67], v[132:135], v[164:167], v[64:67]
	v_mfma_f32_16x16x32_bf16 v[60:63], v[140:143], v[164:167], v[60:63]
	v_mfma_f32_16x16x32_bf16 v[48:51], v[132:135], v[172:175], v[48:51]
	v_mfma_f32_16x16x32_bf16 v[44:47], v[140:143], v[172:175], v[44:47]
	v_mfma_f32_16x16x32_bf16 v[32:35], v[132:135], v[180:183], v[32:35]
	v_mfma_f32_16x16x32_bf16 v[28:31], v[140:143], v[180:183], v[28:31]
	v_mfma_f32_16x16x32_bf16 v[16:19], v[132:135], v[200:203], v[16:19]
	v_mfma_f32_16x16x32_bf16 v[12:15], v[140:143], v[200:203], v[12:15]
	v_mfma_f32_16x16x32_bf16 v[64:67], v[136:139], v[168:171], v[64:67]
	v_mfma_f32_16x16x32_bf16 v[60:63], v[144:147], v[168:171], v[60:63]
	v_mfma_f32_16x16x32_bf16 v[48:51], v[136:139], v[176:179], v[48:51]
	v_mfma_f32_16x16x32_bf16 v[44:47], v[144:147], v[176:179], v[44:47]
	v_mfma_f32_16x16x32_bf16 v[32:35], v[136:139], v[184:187], v[32:35]
	v_mfma_f32_16x16x32_bf16 v[28:31], v[144:147], v[184:187], v[28:31]
	v_mfma_f32_16x16x32_bf16 v[16:19], v[136:139], v[204:207], v[16:19]
	v_mfma_f32_16x16x32_bf16 v[12:15], v[144:147], v[204:207], v[12:15]
	s_setprio 0
	s_setprio 1
	v_mfma_f32_16x16x32_bf16 v[56:59], v[148:151], v[164:167], v[56:59]
	v_mfma_f32_16x16x32_bf16 v[52:55], v[156:159], v[164:167], v[52:55]
	v_mfma_f32_16x16x32_bf16 v[40:43], v[148:151], v[172:175], v[40:43]
	v_mfma_f32_16x16x32_bf16 v[36:39], v[156:159], v[172:175], v[36:39]
	v_mfma_f32_16x16x32_bf16 v[24:27], v[148:151], v[180:183], v[24:27]
	v_mfma_f32_16x16x32_bf16 v[20:23], v[156:159], v[180:183], v[20:23]
	v_mfma_f32_16x16x32_bf16 v[8:11], v[148:151], v[200:203], v[8:11]
	v_mfma_f32_16x16x32_bf16 v[4:7], v[156:159], v[200:203], v[4:7]
	v_mfma_f32_16x16x32_bf16 v[56:59], v[152:155], v[168:171], v[56:59]
	v_mfma_f32_16x16x32_bf16 v[52:55], v[160:163], v[168:171], v[52:55]
	v_mfma_f32_16x16x32_bf16 v[40:43], v[152:155], v[176:179], v[40:43]
	v_mfma_f32_16x16x32_bf16 v[36:39], v[160:163], v[176:179], v[36:39]
	v_mfma_f32_16x16x32_bf16 v[24:27], v[152:155], v[184:187], v[24:27]
	v_mfma_f32_16x16x32_bf16 v[20:23], v[160:163], v[184:187], v[20:23]
	v_mfma_f32_16x16x32_bf16 v[8:11], v[152:155], v[204:207], v[8:11]
	v_mfma_f32_16x16x32_bf16 v[4:7], v[160:163], v[204:207], v[4:7]
	s_setprio 0
	s_barrier
	s_add_i32 s56, 0, 0x18000
	s_add_i32 s57, 0, 0x1c000
	s_add_u32 s22, s22, 0x80000
	s_addc_u32 s23, s23, 0
	s_mov_b32 m0, s31
	v_lshl_add_u64 v[224:225], s[22:23], 0, v[194:195]
	global_load_lds_dwordx4 v[224:225], off
	v_lshl_add_u64 v[224:225], s[22:23], 0, v[190:191]
	s_mov_b32 m0, s34
	s_nop 0
	global_load_lds_dwordx4 v[224:225], off
	v_add_u32_e32 v2, s56, v216
	ds_read_b128 v[132:135], v2
	ds_read_b128 v[136:139], v2 offset:1024
	ds_read_b128 v[140:143], v2 offset:2048
	ds_read_b128 v[144:147], v2 offset:3072
	v_add_u32_e32 v2, s57, v216
	ds_read_b128 v[148:151], v2
	ds_read_b128 v[152:155], v2 offset:1024
	ds_read_b128 v[156:159], v2 offset:2048
	ds_read_b128 v[160:163], v2 offset:3072
	ds_read_b128 v[164:167], v217 offset:32768
	ds_read_b128 v[168:171], v217 offset:33792
	ds_read_b128 v[172:175], v217 offset:34816
	ds_read_b128 v[176:179], v217 offset:35840
	ds_read_b128 v[180:183], v217 offset:36864
	ds_read_b128 v[184:187], v217 offset:37888
	ds_read_b128 v[200:203], v217 offset:38912
	ds_read_b128 v[204:207], v217 offset:39936
	s_waitcnt vmcnt(8)
	s_waitcnt lgkmcnt(0)
	s_barrier
	s_setprio 1
	s_waitcnt lgkmcnt(0)
	v_mfma_f32_16x16x32_bf16 v[128:131], v[132:135], v[164:167], v[128:131]
	v_mfma_f32_16x16x32_bf16 v[124:127], v[140:143], v[164:167], v[124:127]
	v_mfma_f32_16x16x32_bf16 v[112:115], v[132:135], v[172:175], v[112:115]
	v_mfma_f32_16x16x32_bf16 v[108:111], v[140:143], v[172:175], v[108:111]
	v_mfma_f32_16x16x32_bf16 v[96:99], v[132:135], v[180:183], v[96:99]
	v_mfma_f32_16x16x32_bf16 v[92:95], v[140:143], v[180:183], v[92:95]
	v_mfma_f32_16x16x32_bf16 v[80:83], v[132:135], v[200:203], v[80:83]
	v_mfma_f32_16x16x32_bf16 v[76:79], v[140:143], v[200:203], v[76:79]
	v_mfma_f32_16x16x32_bf16 v[128:131], v[136:139], v[168:171], v[128:131]
	v_mfma_f32_16x16x32_bf16 v[124:127], v[144:147], v[168:171], v[124:127]
	v_mfma_f32_16x16x32_bf16 v[112:115], v[136:139], v[176:179], v[112:115]
	v_mfma_f32_16x16x32_bf16 v[108:111], v[144:147], v[176:179], v[108:111]
	v_mfma_f32_16x16x32_bf16 v[96:99], v[136:139], v[184:187], v[96:99]
	v_mfma_f32_16x16x32_bf16 v[92:95], v[144:147], v[184:187], v[92:95]
	v_mfma_f32_16x16x32_bf16 v[80:83], v[136:139], v[204:207], v[80:83]
	v_mfma_f32_16x16x32_bf16 v[76:79], v[144:147], v[204:207], v[76:79]
	s_setprio 0
	s_setprio 1
	v_mfma_f32_16x16x32_bf16 v[120:123], v[148:151], v[164:167], v[120:123]
	v_mfma_f32_16x16x32_bf16 v[116:119], v[156:159], v[164:167], v[116:119]
	v_mfma_f32_16x16x32_bf16 v[104:107], v[148:151], v[172:175], v[104:107]
	v_mfma_f32_16x16x32_bf16 v[100:103], v[156:159], v[172:175], v[100:103]
	v_mfma_f32_16x16x32_bf16 v[88:91], v[148:151], v[180:183], v[88:91]
	v_mfma_f32_16x16x32_bf16 v[84:87], v[156:159], v[180:183], v[84:87]
	v_mfma_f32_16x16x32_bf16 v[72:75], v[148:151], v[200:203], v[72:75]
	v_mfma_f32_16x16x32_bf16 v[68:71], v[156:159], v[200:203], v[68:71]
	v_mfma_f32_16x16x32_bf16 v[120:123], v[152:155], v[168:171], v[120:123]
	v_mfma_f32_16x16x32_bf16 v[116:119], v[160:163], v[168:171], v[116:119]
	v_mfma_f32_16x16x32_bf16 v[104:107], v[152:155], v[176:179], v[104:107]
	v_mfma_f32_16x16x32_bf16 v[100:103], v[160:163], v[176:179], v[100:103]
	v_mfma_f32_16x16x32_bf16 v[88:91], v[152:155], v[184:187], v[88:91]
	v_mfma_f32_16x16x32_bf16 v[84:87], v[160:163], v[184:187], v[84:87]
	v_mfma_f32_16x16x32_bf16 v[72:75], v[152:155], v[204:207], v[72:75]
	v_mfma_f32_16x16x32_bf16 v[68:71], v[160:163], v[204:207], v[68:71]
	s_setprio 0
	s_barrier
	s_add_i32 s22, s56, s28
	v_lshl_add_u64 v[208:209], v[208:209], 0, s[76:77]
	s_mov_b32 m0, s22
	s_nop 0
	global_load_lds_dwordx4 v[208:209], off
	s_add_i32 m0, s22, 0x2000
	s_add_u32 s20, s20, 0x80080
	v_lshl_add_u64 v[208:209], v[210:211], 0, s[76:77]
	s_addc_u32 s21, s21, 0
	s_add_i32 s22, s57, s28
	global_load_lds_dwordx4 v[208:209], off
	v_lshl_add_u64 v[208:209], s[20:21], 0, v[192:193]
	s_mov_b32 m0, s22
	s_nop 0
	global_load_lds_dwordx4 v[208:209], off
	v_lshl_add_u64 v[208:209], s[20:21], 0, v[188:189]
	s_add_i32 m0, s22, 0x2000
	s_nop 0
	global_load_lds_dwordx4 v[208:209], off
	v_lshl_add_u64 v[208:209], v[220:221], 0, s[76:77]
	s_mov_b32 m0, s38
	s_nop 0
	global_load_lds_dwordx4 v[208:209], off
	v_lshl_add_u64 v[208:209], v[222:223], 0, s[76:77]
	s_mov_b32 m0, s39
	s_nop 0
	global_load_lds_dwordx4 v[208:209], off
	ds_read_b128 v[164:167], v217 offset:49152
	ds_read_b128 v[168:171], v217 offset:50176
	ds_read_b128 v[172:175], v217 offset:51200
	ds_read_b128 v[176:179], v217 offset:52224
	ds_read_b128 v[180:183], v217 offset:53248
	ds_read_b128 v[184:187], v217 offset:54272
	ds_read_b128 v[200:203], v217 offset:55296
	ds_read_b128 v[204:207], v217 offset:56320
	s_waitcnt vmcnt(8)
	s_waitcnt lgkmcnt(0)
	s_barrier
	s_setprio 1
	s_waitcnt lgkmcnt(0)
	v_mfma_f32_16x16x32_bf16 v[64:67], v[132:135], v[164:167], v[64:67]
	v_mfma_f32_16x16x32_bf16 v[60:63], v[140:143], v[164:167], v[60:63]
	v_mfma_f32_16x16x32_bf16 v[48:51], v[132:135], v[172:175], v[48:51]
	v_mfma_f32_16x16x32_bf16 v[44:47], v[140:143], v[172:175], v[44:47]
	v_mfma_f32_16x16x32_bf16 v[32:35], v[132:135], v[180:183], v[32:35]
	v_mfma_f32_16x16x32_bf16 v[28:31], v[140:143], v[180:183], v[28:31]
	v_mfma_f32_16x16x32_bf16 v[16:19], v[132:135], v[200:203], v[16:19]
	v_mfma_f32_16x16x32_bf16 v[12:15], v[140:143], v[200:203], v[12:15]
	v_mfma_f32_16x16x32_bf16 v[64:67], v[136:139], v[168:171], v[64:67]
	v_mfma_f32_16x16x32_bf16 v[60:63], v[144:147], v[168:171], v[60:63]
	v_mfma_f32_16x16x32_bf16 v[48:51], v[136:139], v[176:179], v[48:51]
	v_mfma_f32_16x16x32_bf16 v[44:47], v[144:147], v[176:179], v[44:47]
	v_mfma_f32_16x16x32_bf16 v[32:35], v[136:139], v[184:187], v[32:35]
	v_mfma_f32_16x16x32_bf16 v[28:31], v[144:147], v[184:187], v[28:31]
	v_mfma_f32_16x16x32_bf16 v[16:19], v[136:139], v[204:207], v[16:19]
	v_mfma_f32_16x16x32_bf16 v[12:15], v[144:147], v[204:207], v[12:15]
	s_setprio 0
	s_setprio 1
	v_mfma_f32_16x16x32_bf16 v[56:59], v[148:151], v[164:167], v[56:59]
	v_mfma_f32_16x16x32_bf16 v[52:55], v[156:159], v[164:167], v[52:55]
	v_mfma_f32_16x16x32_bf16 v[40:43], v[148:151], v[172:175], v[40:43]
	v_mfma_f32_16x16x32_bf16 v[36:39], v[156:159], v[172:175], v[36:39]
	v_mfma_f32_16x16x32_bf16 v[24:27], v[148:151], v[180:183], v[24:27]
	v_mfma_f32_16x16x32_bf16 v[20:23], v[156:159], v[180:183], v[20:23]
	v_mfma_f32_16x16x32_bf16 v[8:11], v[148:151], v[200:203], v[8:11]
	v_mfma_f32_16x16x32_bf16 v[4:7], v[156:159], v[200:203], v[4:7]
	v_mfma_f32_16x16x32_bf16 v[56:59], v[152:155], v[168:171], v[56:59]
	v_mfma_f32_16x16x32_bf16 v[52:55], v[160:163], v[168:171], v[52:55]
	v_mfma_f32_16x16x32_bf16 v[40:43], v[152:155], v[176:179], v[40:43]
	v_mfma_f32_16x16x32_bf16 v[36:39], v[160:163], v[176:179], v[36:39]
	v_mfma_f32_16x16x32_bf16 v[24:27], v[152:155], v[184:187], v[24:27]
	v_mfma_f32_16x16x32_bf16 v[20:23], v[160:163], v[184:187], v[20:23]
	v_mfma_f32_16x16x32_bf16 v[8:11], v[152:155], v[204:207], v[8:11]
	v_mfma_f32_16x16x32_bf16 v[4:7], v[160:163], v[204:207], v[4:7]
	s_setprio 0
	s_barrier
	s_add_i32 s52, s52, 2
	s_add_u32 s48, s48, 0x100
	s_addc_u32 s49, s49, 0
	s_add_u32 s18, s18, 0x100
	s_addc_u32 s19, s19, 0
	s_cmp_gt_u32 s52, 29
	s_cbranch_scc0 .LBB0_1229
	s_and_b64 vcc, exec, s[8:9]
	s_cbranch_vccz .LBB0_1232
	s_barrier

.LBB0_1336:
	s_add_u32 s10, s8, 0xfff80080
	s_addc_u32 s11, s9, -1
	s_add_i32 s17, 0, 0x10000
	s_cmp_eq_u32 s16, 28
	s_cselect_b32 s15, s18, s11
	s_cselect_b32 s14, s19, s10
	s_cselect_b32 s11, s22, s40
	s_cselect_b32 s10, s23, s39
	s_add_i32 s41, 0, 0x14000
	v_lshl_add_u64 v[196:197], s[8:9], 0, v[232:233]
	s_add_i32 m0, s58, 0xc000
	s_nop 0
	global_load_lds_dwordx4 v[196:197], off
	v_lshl_add_u64 v[196:197], s[8:9], 0, v[230:231]
	s_add_i32 m0, s58, 0xe000
	s_nop 0
	global_load_lds_dwordx4 v[196:197], off
	v_add_u32_e32 v2, s17, v220
	ds_read_b128 v[28:31], v2
	ds_read_b128 v[32:35], v2 offset:1024
	ds_read_b128 v[36:39], v2 offset:2048
	ds_read_b128 v[40:43], v2 offset:3072
	v_add_u32_e32 v2, s41, v220
	ds_read_b128 v[44:47], v2
	ds_read_b128 v[48:51], v2 offset:1024
	ds_read_b128 v[52:55], v2 offset:2048
	ds_read_b128 v[56:59], v2 offset:3072
	ds_read_b128 v[92:95], v216
	ds_read_b128 v[96:99], v216 offset:1024
	ds_read_b128 v[100:103], v216 offset:2048
	ds_read_b128 v[104:107], v216 offset:3072
	ds_read_b128 v[108:111], v216 offset:4096
	ds_read_b128 v[112:115], v216 offset:5120
	ds_read_b128 v[116:119], v216 offset:6144
	ds_read_b128 v[120:123], v216 offset:7168
	s_waitcnt vmcnt(8)
	s_waitcnt lgkmcnt(0)
	s_barrier
	s_setprio 1
	s_waitcnt lgkmcnt(0)
	v_mfma_f32_16x16x32_bf16 v[192:195], v[28:31], v[92:95], v[192:195]
	v_mfma_f32_16x16x32_bf16 v[160:163], v[36:39], v[92:95], v[160:163]
	v_mfma_f32_16x16x32_bf16 v[188:191], v[28:31], v[100:103], v[188:191]
	v_mfma_f32_16x16x32_bf16 v[152:155], v[36:39], v[100:103], v[152:155]
	v_mfma_f32_16x16x32_bf16 v[176:179], v[28:31], v[108:111], v[176:179]
	v_mfma_f32_16x16x32_bf16 v[144:147], v[36:39], v[108:111], v[144:147]
	v_mfma_f32_16x16x32_bf16 v[168:171], v[28:31], v[116:119], v[168:171]
	v_mfma_f32_16x16x32_bf16 v[136:139], v[36:39], v[116:119], v[136:139]
	v_mfma_f32_16x16x32_bf16 v[192:195], v[32:35], v[96:99], v[192:195]
	v_mfma_f32_16x16x32_bf16 v[160:163], v[40:43], v[96:99], v[160:163]
	v_mfma_f32_16x16x32_bf16 v[188:191], v[32:35], v[104:107], v[188:191]
	v_mfma_f32_16x16x32_bf16 v[152:155], v[40:43], v[104:107], v[152:155]
	v_mfma_f32_16x16x32_bf16 v[176:179], v[32:35], v[112:115], v[176:179]
	v_mfma_f32_16x16x32_bf16 v[144:147], v[40:43], v[112:115], v[144:147]
	v_mfma_f32_16x16x32_bf16 v[168:171], v[32:35], v[120:123], v[168:171]
	v_mfma_f32_16x16x32_bf16 v[136:139], v[40:43], v[120:123], v[136:139]
	s_setprio 0
	s_setprio 1
	v_mfma_f32_16x16x32_bf16 v[180:183], v[44:47], v[92:95], v[180:183]
	v_mfma_f32_16x16x32_bf16 v[92:95], v[52:55], v[92:95], v[156:159]
	v_mfma_f32_16x16x32_bf16 v[180:183], v[48:51], v[96:99], v[180:183]
	v_mfma_f32_16x16x32_bf16 v[92:95], v[56:59], v[96:99], v[92:95]
	v_mfma_f32_16x16x32_bf16 v[96:99], v[44:47], v[100:103], v[184:187]
	v_mfma_f32_16x16x32_bf16 v[100:103], v[52:55], v[100:103], v[148:151]
	v_mfma_f32_16x16x32_bf16 v[96:99], v[48:51], v[104:107], v[96:99]
	v_mfma_f32_16x16x32_bf16 v[100:103], v[56:59], v[104:107], v[100:103]
	v_mfma_f32_16x16x32_bf16 v[104:107], v[44:47], v[108:111], v[172:175]
	v_mfma_f32_16x16x32_bf16 v[108:111], v[52:55], v[108:111], v[140:143]
	v_mfma_f32_16x16x32_bf16 v[104:107], v[48:51], v[112:115], v[104:107]
	v_mfma_f32_16x16x32_bf16 v[108:111], v[56:59], v[112:115], v[108:111]
	v_mfma_f32_16x16x32_bf16 v[112:115], v[44:47], v[116:119], v[164:167]
	v_mfma_f32_16x16x32_bf16 v[116:119], v[52:55], v[116:119], v[132:135]
	v_mfma_f32_16x16x32_bf16 v[112:115], v[48:51], v[120:123], v[112:115]
	v_mfma_f32_16x16x32_bf16 v[116:119], v[56:59], v[120:123], v[116:119]
	s_setprio 0
	s_barrier
	s_add_i32 s17, s17, s54
	v_lshl_add_u64 v[234:235], s[10:11], 0, v[226:227]
	s_mov_b32 m0, s17
	s_nop 0
	global_load_lds_dwordx4 v[234:235], off
	s_add_i32 m0, s17, 0x2000
	s_add_u32 s42, s10, 0x80000
	v_lshl_add_u64 v[236:237], s[10:11], 0, v[222:223]
	s_addc_u32 s43, s11, 0
	s_add_i32 s17, s41, s54
	global_load_lds_dwordx4 v[236:237], off
	v_lshl_add_u64 v[196:197], s[42:43], 0, v[226:227]
	s_mov_b32 m0, s17
	v_lshl_add_u64 v[238:239], s[14:15], 0, v[228:229]
	global_load_lds_dwordx4 v[196:197], off
	v_lshl_add_u64 v[196:197], s[42:43], 0, v[222:223]
	s_add_i32 m0, s17, 0x2000
	v_lshl_add_u64 v[240:241], s[14:15], 0, v[224:225]
	global_load_lds_dwordx4 v[196:197], off
	s_mov_b32 m0, s58
	s_nop 0
	global_load_lds_dwordx4 v[238:239], off
	s_mov_b32 m0, s59
	s_nop 0
	global_load_lds_dwordx4 v[240:241], off
	ds_read_b128 v[120:123], v216 offset:16384
	ds_read_b128 v[132:135], v216 offset:17408
	ds_read_b128 v[140:143], v216 offset:18432
	ds_read_b128 v[148:151], v216 offset:19456
	ds_read_b128 v[156:159], v216 offset:20480
	ds_read_b128 v[164:167], v216 offset:21504
	ds_read_b128 v[172:175], v216 offset:22528
	ds_read_b128 v[184:187], v216 offset:23552
	s_waitcnt vmcnt(8)
	s_waitcnt lgkmcnt(0)
	s_barrier
	s_setprio 1
	s_waitcnt lgkmcnt(0)
	v_mfma_f32_16x16x32_bf16 v[128:131], v[28:31], v[120:123], v[128:131]
	v_mfma_f32_16x16x32_bf16 v[64:67], v[36:39], v[120:123], v[64:67]
	v_mfma_f32_16x16x32_bf16 v[88:91], v[28:31], v[140:143], v[88:91]
	v_mfma_f32_16x16x32_bf16 v[24:27], v[36:39], v[140:143], v[24:27]
	v_mfma_f32_16x16x32_bf16 v[80:83], v[28:31], v[156:159], v[80:83]
	v_mfma_f32_16x16x32_bf16 v[16:19], v[36:39], v[156:159], v[16:19]
	v_mfma_f32_16x16x32_bf16 v[8:11], v[36:39], v[172:175], v[8:11]
	v_mfma_f32_16x16x32_bf16 v[128:131], v[32:35], v[132:135], v[128:131]
	v_mfma_f32_16x16x32_bf16 v[64:67], v[40:43], v[132:135], v[64:67]
	v_mfma_f32_16x16x32_bf16 v[88:91], v[32:35], v[148:151], v[88:91]
	v_mfma_f32_16x16x32_bf16 v[24:27], v[40:43], v[148:151], v[24:27]
	v_mfma_f32_16x16x32_bf16 v[80:83], v[32:35], v[164:167], v[80:83]
	v_mfma_f32_16x16x32_bf16 v[16:19], v[40:43], v[164:167], v[16:19]
	v_mfma_f32_16x16x32_bf16 v[28:31], v[28:31], v[172:175], v[72:75]
	v_mfma_f32_16x16x32_bf16 v[8:11], v[40:43], v[184:187], v[8:11]
	v_mfma_f32_16x16x32_bf16 v[28:31], v[32:35], v[184:187], v[28:31]
	s_setprio 0
	s_setprio 1
	v_mfma_f32_16x16x32_bf16 v[36:39], v[52:55], v[120:123], v[60:63]
	v_mfma_f32_16x16x32_bf16 v[20:23], v[52:55], v[140:143], v[20:23]
	v_mfma_f32_16x16x32_bf16 v[60:63], v[44:47], v[156:159], v[76:79]
	v_mfma_f32_16x16x32_bf16 v[12:15], v[52:55], v[156:159], v[12:15]
	v_mfma_f32_16x16x32_bf16 v[4:7], v[52:55], v[172:175], v[4:7]
	v_mfma_f32_16x16x32_bf16 v[32:35], v[44:47], v[120:123], v[124:127]
	v_mfma_f32_16x16x32_bf16 v[40:43], v[44:47], v[140:143], v[84:87]
	v_mfma_f32_16x16x32_bf16 v[20:23], v[56:59], v[148:151], v[20:23]
	v_mfma_f32_16x16x32_bf16 v[76:79], v[48:51], v[164:167], v[60:63]
	v_mfma_f32_16x16x32_bf16 v[12:15], v[56:59], v[164:167], v[12:15]
	v_mfma_f32_16x16x32_bf16 v[44:47], v[44:47], v[172:175], v[68:71]
	v_mfma_f32_16x16x32_bf16 v[4:7], v[56:59], v[184:187], v[4:7]
	v_mfma_f32_16x16x32_bf16 v[32:35], v[48:51], v[132:135], v[32:35]
	v_mfma_f32_16x16x32_bf16 v[36:39], v[56:59], v[132:135], v[36:39]
	v_mfma_f32_16x16x32_bf16 v[40:43], v[48:51], v[148:151], v[40:43]
	v_mfma_f32_16x16x32_bf16 v[44:47], v[48:51], v[184:187], v[44:47]
	s_setprio 0
	s_barrier
	s_add_i32 s17, 0, 0x18000
	s_add_i32 s41, 0, 0x1c000
	s_add_u32 s14, s14, 0x80000
	s_addc_u32 s15, s15, 0
	s_mov_b32 m0, s60
	v_lshl_add_u64 v[148:149], s[14:15], 0, v[228:229]
	global_load_lds_dwordx4 v[148:149], off
	v_lshl_add_u64 v[148:149], s[14:15], 0, v[224:225]
	s_mov_b32 m0, s61
	s_nop 0
	global_load_lds_dwordx4 v[148:149], off
	v_add_u32_e32 v2, s17, v220
	ds_read_b128 v[48:51], v2
	ds_read_b128 v[52:55], v2 offset:1024
	ds_read_b128 v[56:59], v2 offset:2048
	ds_read_b128 v[60:63], v2 offset:3072
	v_add_u32_e32 v2, s41, v220
	ds_read_b128 v[68:71], v2
	ds_read_b128 v[120:123], v2 offset:1024
	ds_read_b128 v[196:199], v2 offset:2048
	ds_read_b128 v[200:203], v2 offset:3072
	ds_read_b128 v[72:75], v216 offset:32768
	ds_read_b128 v[84:87], v216 offset:33792
	ds_read_b128 v[124:127], v216 offset:34816
	ds_read_b128 v[132:135], v216 offset:35840
	ds_read_b128 v[140:143], v216 offset:36864
	ds_read_b128 v[164:167], v216 offset:37888
	ds_read_b128 v[204:207], v216 offset:38912
	ds_read_b128 v[208:211], v216 offset:39936
	s_waitcnt vmcnt(8)
	s_waitcnt lgkmcnt(0)
	s_barrier
	s_setprio 1
	s_waitcnt lgkmcnt(0)
	v_mfma_f32_16x16x32_bf16 v[148:151], v[48:51], v[72:75], v[192:195]
	v_mfma_f32_16x16x32_bf16 v[192:195], v[52:55], v[84:87], v[148:151]
	v_mfma_f32_16x16x32_bf16 v[148:151], v[56:59], v[72:75], v[160:163]
	v_mfma_f32_16x16x32_bf16 v[160:163], v[60:63], v[84:87], v[148:151]
	v_mfma_f32_16x16x32_bf16 v[148:151], v[48:51], v[124:127], v[188:191]
	v_mfma_f32_16x16x32_bf16 v[188:191], v[52:55], v[132:135], v[148:151]
	v_mfma_f32_16x16x32_bf16 v[148:151], v[56:59], v[124:127], v[152:155]
	v_mfma_f32_16x16x32_bf16 v[152:155], v[60:63], v[132:135], v[148:151]
	v_mfma_f32_16x16x32_bf16 v[148:151], v[48:51], v[140:143], v[176:179]
	v_mfma_f32_16x16x32_bf16 v[176:179], v[52:55], v[164:167], v[148:151]
	v_mfma_f32_16x16x32_bf16 v[144:147], v[56:59], v[140:143], v[144:147]
	v_mfma_f32_16x16x32_bf16 v[148:151], v[48:51], v[204:207], v[168:171]
	v_mfma_f32_16x16x32_bf16 v[136:139], v[56:59], v[204:207], v[136:139]
	v_mfma_f32_16x16x32_bf16 v[144:147], v[60:63], v[164:167], v[144:147]
	v_mfma_f32_16x16x32_bf16 v[168:171], v[52:55], v[208:211], v[148:151]
	v_mfma_f32_16x16x32_bf16 v[136:139], v[60:63], v[208:211], v[136:139]
	s_setprio 0
	s_setprio 1
	v_mfma_f32_16x16x32_bf16 v[148:151], v[68:71], v[72:75], v[180:183]
	v_mfma_f32_16x16x32_bf16 v[72:75], v[196:199], v[72:75], v[92:95]
	v_mfma_f32_16x16x32_bf16 v[156:159], v[200:203], v[84:87], v[72:75]
	v_mfma_f32_16x16x32_bf16 v[72:75], v[68:71], v[124:127], v[96:99]
	v_mfma_f32_16x16x32_bf16 v[184:187], v[120:123], v[132:135], v[72:75]
	v_mfma_f32_16x16x32_bf16 v[72:75], v[196:199], v[124:127], v[100:103]
	v_mfma_f32_16x16x32_bf16 v[180:183], v[120:123], v[84:87], v[148:151]
	v_mfma_f32_16x16x32_bf16 v[148:151], v[200:203], v[132:135], v[72:75]
	v_mfma_f32_16x16x32_bf16 v[72:75], v[68:71], v[140:143], v[104:107]
	v_mfma_f32_16x16x32_bf16 v[172:175], v[120:123], v[164:167], v[72:75]
	v_mfma_f32_16x16x32_bf16 v[72:75], v[196:199], v[140:143], v[108:111]
	v_mfma_f32_16x16x32_bf16 v[140:143], v[200:203], v[164:167], v[72:75]
	v_mfma_f32_16x16x32_bf16 v[72:75], v[68:71], v[204:207], v[112:115]
	v_mfma_f32_16x16x32_bf16 v[164:167], v[120:123], v[208:211], v[72:75]
	v_mfma_f32_16x16x32_bf16 v[72:75], v[196:199], v[204:207], v[116:119]
	v_mfma_f32_16x16x32_bf16 v[132:135], v[200:203], v[208:211], v[72:75]
	s_setprio 0
	s_barrier
	s_add_i32 s14, s17, s54
	s_nop 3
	v_lshl_add_u64 v[72:73], v[234:235], 0, s[20:21]
	s_mov_b32 m0, s14
	s_nop 0
	global_load_lds_dwordx4 v[72:73], off
	s_add_i32 m0, s14, 0x2000
	s_add_u32 s10, s10, 0x80080
	v_lshl_add_u64 v[72:73], v[236:237], 0, s[20:21]
	s_addc_u32 s11, s11, 0
	s_add_i32 s14, s41, s54
	global_load_lds_dwordx4 v[72:73], off
	v_lshl_add_u64 v[72:73], s[10:11], 0, v[226:227]
	s_mov_b32 m0, s14
	s_nop 0
	global_load_lds_dwordx4 v[72:73], off
	v_lshl_add_u64 v[72:73], s[10:11], 0, v[222:223]
	s_add_i32 m0, s14, 0x2000
	s_nop 0
	global_load_lds_dwordx4 v[72:73], off
	v_lshl_add_u64 v[72:73], v[238:239], 0, s[20:21]
	s_mov_b32 m0, s65
	s_nop 0
	global_load_lds_dwordx4 v[72:73], off
	v_lshl_add_u64 v[72:73], v[240:241], 0, s[20:21]
	s_mov_b32 m0, s66
	s_nop 0
	global_load_lds_dwordx4 v[72:73], off
	ds_read_b128 v[84:87], v216 offset:49152
	ds_read_b128 v[92:95], v216 offset:50176
	ds_read_b128 v[96:99], v216 offset:51200
	ds_read_b128 v[100:103], v216 offset:52224
	ds_read_b128 v[104:107], v216 offset:53248
	ds_read_b128 v[108:111], v216 offset:54272
	ds_read_b128 v[112:115], v216 offset:55296
	ds_read_b128 v[116:119], v216 offset:56320
	s_waitcnt vmcnt(8)
	s_waitcnt lgkmcnt(0)
	s_barrier
	s_setprio 1
	s_waitcnt lgkmcnt(0)
	v_mfma_f32_16x16x32_bf16 v[72:75], v[48:51], v[84:87], v[128:131]
	v_mfma_f32_16x16x32_bf16 v[128:131], v[52:55], v[92:95], v[72:75]
	v_mfma_f32_16x16x32_bf16 v[72:75], v[48:51], v[96:99], v[88:91]
	v_mfma_f32_16x16x32_bf16 v[64:67], v[56:59], v[84:87], v[64:67]
	v_mfma_f32_16x16x32_bf16 v[88:91], v[52:55], v[100:103], v[72:75]
	v_mfma_f32_16x16x32_bf16 v[24:27], v[56:59], v[96:99], v[24:27]
	v_mfma_f32_16x16x32_bf16 v[72:75], v[48:51], v[104:107], v[80:83]
	v_mfma_f32_16x16x32_bf16 v[16:19], v[56:59], v[104:107], v[16:19]
	v_mfma_f32_16x16x32_bf16 v[28:31], v[48:51], v[112:115], v[28:31]
	v_mfma_f32_16x16x32_bf16 v[8:11], v[56:59], v[112:115], v[8:11]
	v_mfma_f32_16x16x32_bf16 v[64:67], v[60:63], v[92:95], v[64:67]
	v_mfma_f32_16x16x32_bf16 v[24:27], v[60:63], v[100:103], v[24:27]
	v_mfma_f32_16x16x32_bf16 v[80:83], v[52:55], v[108:111], v[72:75]
	v_mfma_f32_16x16x32_bf16 v[16:19], v[60:63], v[108:111], v[16:19]
	v_mfma_f32_16x16x32_bf16 v[72:75], v[52:55], v[116:119], v[28:31]
	v_mfma_f32_16x16x32_bf16 v[8:11], v[60:63], v[116:119], v[8:11]
	s_setprio 0
	s_setprio 1
	v_mfma_f32_16x16x32_bf16 v[28:31], v[68:71], v[84:87], v[32:35]
	v_mfma_f32_16x16x32_bf16 v[124:127], v[120:123], v[92:95], v[28:31]
	v_mfma_f32_16x16x32_bf16 v[28:31], v[196:199], v[84:87], v[36:39]
	v_mfma_f32_16x16x32_bf16 v[60:63], v[200:203], v[92:95], v[28:31]
	v_mfma_f32_16x16x32_bf16 v[28:31], v[68:71], v[96:99], v[40:43]
	v_mfma_f32_16x16x32_bf16 v[84:87], v[120:123], v[100:103], v[28:31]
	v_mfma_f32_16x16x32_bf16 v[28:31], v[68:71], v[104:107], v[76:79]
	v_mfma_f32_16x16x32_bf16 v[20:23], v[196:199], v[96:99], v[20:23]
	v_mfma_f32_16x16x32_bf16 v[76:79], v[120:123], v[108:111], v[28:31]
	v_mfma_f32_16x16x32_bf16 v[12:15], v[196:199], v[104:107], v[12:15]
	v_mfma_f32_16x16x32_bf16 v[28:31], v[68:71], v[112:115], v[44:47]
	v_mfma_f32_16x16x32_bf16 v[4:7], v[196:199], v[112:115], v[4:7]
	v_mfma_f32_16x16x32_bf16 v[20:23], v[200:203], v[100:103], v[20:23]
	v_mfma_f32_16x16x32_bf16 v[12:15], v[200:203], v[108:111], v[12:15]
	v_mfma_f32_16x16x32_bf16 v[68:71], v[120:123], v[116:119], v[28:31]
	v_mfma_f32_16x16x32_bf16 v[4:7], v[200:203], v[116:119], v[4:7]
	s_setprio 0
	s_barrier
	s_add_i32 s16, s16, 2
	s_add_u32 s39, s39, 0x100
	s_addc_u32 s40, s40, 0
	s_add_u32 s8, s8, 0x100
	s_addc_u32 s9, s9, 0
	s_cmp_gt_u32 s16, 29
	s_cbranch_scc0 .LBB0_1336
	v_readlane_b32 s8, v255, 6
	v_readlane_b32 s9, v255, 7
	s_and_b64 vcc, exec, s[8:9]
	s_mov_b32 s81, 0xb000
	s_cbranch_vccz .LBB0_1339
	s_barrier

.LBB0_1504:
	s_add_u32 s4, s22, 0x100
	s_addc_u32 s5, s23, 0
	s_add_i32 s58, 0, 0x10000
	s_cmpk_eq_i32 s57, 0x54
	s_cselect_b32 s27, s19, s5
	s_cselect_b32 s26, s18, s4
	s_cselect_b32 s25, s21, s56
	s_cselect_b32 s24, s20, s52
	s_add_i32 s59, 0, 0x14000
	v_lshl_add_u64 v[208:209], s[22:23], 0, v[198:199]
	s_add_i32 m0, s31, 0xc000
	s_nop 0
	global_load_lds_dwordx4 v[208:209], off
	v_lshl_add_u64 v[208:209], s[22:23], 0, v[196:197]
	s_add_i32 m0, s31, 0xe000
	s_nop 0
	global_load_lds_dwordx4 v[208:209], off
	v_add_u32_e32 v2, s58, v216
	ds_read_b128 v[124:127], v2
	ds_read_b128 v[128:131], v2 offset:1024
	ds_read_b128 v[132:135], v2 offset:2048
	ds_read_b128 v[136:139], v2 offset:3072
	v_add_u32_e32 v2, s59, v216
	ds_read_b128 v[148:151], v2
	ds_read_b128 v[152:155], v2 offset:1024
	ds_read_b128 v[156:159], v2 offset:2048
	ds_read_b128 v[160:163], v2 offset:3072
	ds_read_b128 v[164:167], v217
	ds_read_b128 v[168:171], v217 offset:1024
	ds_read_b128 v[172:175], v217 offset:2048
	ds_read_b128 v[176:179], v217 offset:3072
	ds_read_b128 v[180:183], v217 offset:4096
	ds_read_b128 v[184:187], v217 offset:5120
	ds_read_b128 v[200:203], v217 offset:6144
	ds_read_b128 v[204:207], v217 offset:7168
	s_waitcnt vmcnt(8)
	s_waitcnt lgkmcnt(0)
	s_barrier
	s_setprio 1
	s_waitcnt lgkmcnt(0)
	v_mfma_f32_16x16x32_bf16 v[144:147], v[124:127], v[164:167], v[144:147]
	v_mfma_f32_16x16x32_bf16 v[140:143], v[132:135], v[164:167], v[140:143]
	v_mfma_f32_16x16x32_bf16 v[112:115], v[124:127], v[172:175], v[112:115]
	v_mfma_f32_16x16x32_bf16 v[108:111], v[132:135], v[172:175], v[108:111]
	v_mfma_f32_16x16x32_bf16 v[96:99], v[124:127], v[180:183], v[96:99]
	v_mfma_f32_16x16x32_bf16 v[92:95], v[132:135], v[180:183], v[92:95]
	v_mfma_f32_16x16x32_bf16 v[80:83], v[124:127], v[200:203], v[80:83]
	v_mfma_f32_16x16x32_bf16 v[76:79], v[132:135], v[200:203], v[76:79]
	v_mfma_f32_16x16x32_bf16 v[144:147], v[128:131], v[168:171], v[144:147]
	v_mfma_f32_16x16x32_bf16 v[140:143], v[136:139], v[168:171], v[140:143]
	v_mfma_f32_16x16x32_bf16 v[112:115], v[128:131], v[176:179], v[112:115]
	v_mfma_f32_16x16x32_bf16 v[108:111], v[136:139], v[176:179], v[108:111]
	v_mfma_f32_16x16x32_bf16 v[96:99], v[128:131], v[184:187], v[96:99]
	v_mfma_f32_16x16x32_bf16 v[92:95], v[136:139], v[184:187], v[92:95]
	v_mfma_f32_16x16x32_bf16 v[80:83], v[128:131], v[204:207], v[80:83]
	v_mfma_f32_16x16x32_bf16 v[76:79], v[136:139], v[204:207], v[76:79]
	s_setprio 0
	s_setprio 1
	v_mfma_f32_16x16x32_bf16 v[120:123], v[148:151], v[164:167], v[120:123]
	v_mfma_f32_16x16x32_bf16 v[116:119], v[156:159], v[164:167], v[116:119]
	v_mfma_f32_16x16x32_bf16 v[104:107], v[148:151], v[172:175], v[104:107]
	v_mfma_f32_16x16x32_bf16 v[100:103], v[156:159], v[172:175], v[100:103]
	v_mfma_f32_16x16x32_bf16 v[88:91], v[148:151], v[180:183], v[88:91]
	v_mfma_f32_16x16x32_bf16 v[84:87], v[156:159], v[180:183], v[84:87]
	v_mfma_f32_16x16x32_bf16 v[72:75], v[148:151], v[200:203], v[72:75]
	v_mfma_f32_16x16x32_bf16 v[68:71], v[156:159], v[200:203], v[68:71]
	v_mfma_f32_16x16x32_bf16 v[120:123], v[152:155], v[168:171], v[120:123]
	v_mfma_f32_16x16x32_bf16 v[116:119], v[160:163], v[168:171], v[116:119]
	v_mfma_f32_16x16x32_bf16 v[104:107], v[152:155], v[176:179], v[104:107]
	v_mfma_f32_16x16x32_bf16 v[100:103], v[160:163], v[176:179], v[100:103]
	v_mfma_f32_16x16x32_bf16 v[88:91], v[152:155], v[184:187], v[88:91]
	v_mfma_f32_16x16x32_bf16 v[84:87], v[160:163], v[184:187], v[84:87]
	v_mfma_f32_16x16x32_bf16 v[72:75], v[152:155], v[204:207], v[72:75]
	v_mfma_f32_16x16x32_bf16 v[68:71], v[160:163], v[204:207], v[68:71]
	s_setprio 0
	s_barrier
	s_add_i32 s22, s58, s28
	v_lshl_add_u64 v[208:209], s[24:25], 0, v[192:193]
	s_mov_b32 m0, s22
	s_nop 0
	global_load_lds_dwordx4 v[208:209], off
	s_add_i32 m0, s22, 0x2000
	s_add_u32 s22, s24, 0x160000
	v_lshl_add_u64 v[210:211], s[24:25], 0, v[188:189]
	s_addc_u32 s23, s25, 0
	s_add_i32 s58, s59, s28
	global_load_lds_dwordx4 v[210:211], off
	v_lshl_add_u64 v[220:221], s[22:23], 0, v[192:193]
	s_mov_b32 m0, s58
	v_lshl_add_u64 v[222:223], s[26:27], 0, v[190:191]
	global_load_lds_dwordx4 v[220:221], off
	v_lshl_add_u64 v[220:221], s[22:23], 0, v[188:189]
	s_add_i32 m0, s58, 0x2000
	s_nop 0
	global_load_lds_dwordx4 v[220:221], off
	v_lshl_add_u64 v[220:221], s[26:27], 0, v[194:195]
	s_mov_b32 m0, s31
	s_nop 0
	global_load_lds_dwordx4 v[220:221], off
	s_mov_b32 m0, s34
	s_nop 0
	global_load_lds_dwordx4 v[222:223], off
	ds_read_b128 v[164:167], v217 offset:16384
	ds_read_b128 v[168:171], v217 offset:17408
	ds_read_b128 v[172:175], v217 offset:18432
	ds_read_b128 v[176:179], v217 offset:19456
	ds_read_b128 v[180:183], v217 offset:20480
	ds_read_b128 v[184:187], v217 offset:21504
	ds_read_b128 v[200:203], v217 offset:22528
	ds_read_b128 v[204:207], v217 offset:23552
	s_waitcnt vmcnt(8)
	s_waitcnt lgkmcnt(0)
	s_barrier
	s_setprio 1
	s_waitcnt lgkmcnt(0)
	v_mfma_f32_16x16x32_bf16 v[64:67], v[124:127], v[164:167], v[64:67]
	v_mfma_f32_16x16x32_bf16 v[60:63], v[132:135], v[164:167], v[60:63]
	v_mfma_f32_16x16x32_bf16 v[48:51], v[124:127], v[172:175], v[48:51]
	v_mfma_f32_16x16x32_bf16 v[44:47], v[132:135], v[172:175], v[44:47]
	v_mfma_f32_16x16x32_bf16 v[32:35], v[124:127], v[180:183], v[32:35]
	v_mfma_f32_16x16x32_bf16 v[28:31], v[132:135], v[180:183], v[28:31]
	v_mfma_f32_16x16x32_bf16 v[16:19], v[124:127], v[200:203], v[16:19]
	v_mfma_f32_16x16x32_bf16 v[12:15], v[132:135], v[200:203], v[12:15]
	v_mfma_f32_16x16x32_bf16 v[64:67], v[128:131], v[168:171], v[64:67]
	v_mfma_f32_16x16x32_bf16 v[60:63], v[136:139], v[168:171], v[60:63]
	v_mfma_f32_16x16x32_bf16 v[48:51], v[128:131], v[176:179], v[48:51]
	v_mfma_f32_16x16x32_bf16 v[44:47], v[136:139], v[176:179], v[44:47]
	v_mfma_f32_16x16x32_bf16 v[32:35], v[128:131], v[184:187], v[32:35]
	v_mfma_f32_16x16x32_bf16 v[28:31], v[136:139], v[184:187], v[28:31]
	v_mfma_f32_16x16x32_bf16 v[16:19], v[128:131], v[204:207], v[16:19]
	v_mfma_f32_16x16x32_bf16 v[12:15], v[136:139], v[204:207], v[12:15]
	s_setprio 0
	s_setprio 1
	v_mfma_f32_16x16x32_bf16 v[56:59], v[148:151], v[164:167], v[56:59]
	v_mfma_f32_16x16x32_bf16 v[52:55], v[156:159], v[164:167], v[52:55]
	v_mfma_f32_16x16x32_bf16 v[40:43], v[148:151], v[172:175], v[40:43]
	v_mfma_f32_16x16x32_bf16 v[36:39], v[156:159], v[172:175], v[36:39]
	v_mfma_f32_16x16x32_bf16 v[24:27], v[148:151], v[180:183], v[24:27]
	v_mfma_f32_16x16x32_bf16 v[20:23], v[156:159], v[180:183], v[20:23]
	v_mfma_f32_16x16x32_bf16 v[8:11], v[148:151], v[200:203], v[8:11]
	v_mfma_f32_16x16x32_bf16 v[4:7], v[156:159], v[200:203], v[4:7]
	v_mfma_f32_16x16x32_bf16 v[56:59], v[152:155], v[168:171], v[56:59]
	v_mfma_f32_16x16x32_bf16 v[52:55], v[160:163], v[168:171], v[52:55]
	v_mfma_f32_16x16x32_bf16 v[40:43], v[152:155], v[176:179], v[40:43]
	v_mfma_f32_16x16x32_bf16 v[36:39], v[160:163], v[176:179], v[36:39]
	v_mfma_f32_16x16x32_bf16 v[24:27], v[152:155], v[184:187], v[24:27]
	v_mfma_f32_16x16x32_bf16 v[20:23], v[160:163], v[184:187], v[20:23]
	v_mfma_f32_16x16x32_bf16 v[8:11], v[152:155], v[204:207], v[8:11]
	v_mfma_f32_16x16x32_bf16 v[4:7], v[160:163], v[204:207], v[4:7]
	s_setprio 0
	s_barrier
	s_add_i32 s58, 0, 0x18000
	s_add_i32 s59, 0, 0x1c000
	s_add_u32 s22, s26, 0x160000
	s_addc_u32 s23, s27, 0
	s_mov_b32 m0, s35
	v_lshl_add_u64 v[224:225], s[22:23], 0, v[194:195]
	global_load_lds_dwordx4 v[224:225], off
	v_lshl_add_u64 v[224:225], s[22:23], 0, v[190:191]
	s_mov_b32 m0, s36
	s_nop 0
	global_load_lds_dwordx4 v[224:225], off
	v_add_u32_e32 v2, s58, v216
	ds_read_b128 v[124:127], v2
	ds_read_b128 v[128:131], v2 offset:1024
	ds_read_b128 v[132:135], v2 offset:2048
	ds_read_b128 v[136:139], v2 offset:3072
	v_add_u32_e32 v2, s59, v216
	ds_read_b128 v[148:151], v2
	ds_read_b128 v[152:155], v2 offset:1024
	ds_read_b128 v[156:159], v2 offset:2048
	ds_read_b128 v[160:163], v2 offset:3072
	ds_read_b128 v[164:167], v217 offset:32768
	ds_read_b128 v[168:171], v217 offset:33792
	ds_read_b128 v[172:175], v217 offset:34816
	ds_read_b128 v[176:179], v217 offset:35840
	ds_read_b128 v[180:183], v217 offset:36864
	ds_read_b128 v[184:187], v217 offset:37888
	ds_read_b128 v[200:203], v217 offset:38912
	ds_read_b128 v[204:207], v217 offset:39936
	s_waitcnt vmcnt(8)
	s_waitcnt lgkmcnt(0)
	s_barrier
	s_setprio 1
	s_waitcnt lgkmcnt(0)
	v_mfma_f32_16x16x32_bf16 v[144:147], v[124:127], v[164:167], v[144:147]
	v_mfma_f32_16x16x32_bf16 v[140:143], v[132:135], v[164:167], v[140:143]
	v_mfma_f32_16x16x32_bf16 v[112:115], v[124:127], v[172:175], v[112:115]
	v_mfma_f32_16x16x32_bf16 v[108:111], v[132:135], v[172:175], v[108:111]
	v_mfma_f32_16x16x32_bf16 v[96:99], v[124:127], v[180:183], v[96:99]
	v_mfma_f32_16x16x32_bf16 v[92:95], v[132:135], v[180:183], v[92:95]
	v_mfma_f32_16x16x32_bf16 v[80:83], v[124:127], v[200:203], v[80:83]
	v_mfma_f32_16x16x32_bf16 v[76:79], v[132:135], v[200:203], v[76:79]
	v_mfma_f32_16x16x32_bf16 v[144:147], v[128:131], v[168:171], v[144:147]
	v_mfma_f32_16x16x32_bf16 v[140:143], v[136:139], v[168:171], v[140:143]
	v_mfma_f32_16x16x32_bf16 v[112:115], v[128:131], v[176:179], v[112:115]
	v_mfma_f32_16x16x32_bf16 v[108:111], v[136:139], v[176:179], v[108:111]
	v_mfma_f32_16x16x32_bf16 v[96:99], v[128:131], v[184:187], v[96:99]
	v_mfma_f32_16x16x32_bf16 v[92:95], v[136:139], v[184:187], v[92:95]
	v_mfma_f32_16x16x32_bf16 v[80:83], v[128:131], v[204:207], v[80:83]
	v_mfma_f32_16x16x32_bf16 v[76:79], v[136:139], v[204:207], v[76:79]
	s_setprio 0
	s_setprio 1
	v_mfma_f32_16x16x32_bf16 v[120:123], v[148:151], v[164:167], v[120:123]
	v_mfma_f32_16x16x32_bf16 v[116:119], v[156:159], v[164:167], v[116:119]
	v_mfma_f32_16x16x32_bf16 v[104:107], v[148:151], v[172:175], v[104:107]
	v_mfma_f32_16x16x32_bf16 v[100:103], v[156:159], v[172:175], v[100:103]
	v_mfma_f32_16x16x32_bf16 v[88:91], v[148:151], v[180:183], v[88:91]
	v_mfma_f32_16x16x32_bf16 v[84:87], v[156:159], v[180:183], v[84:87]
	v_mfma_f32_16x16x32_bf16 v[72:75], v[148:151], v[200:203], v[72:75]
	v_mfma_f32_16x16x32_bf16 v[68:71], v[156:159], v[200:203], v[68:71]
	v_mfma_f32_16x16x32_bf16 v[120:123], v[152:155], v[168:171], v[120:123]
	v_mfma_f32_16x16x32_bf16 v[116:119], v[160:163], v[168:171], v[116:119]
	v_mfma_f32_16x16x32_bf16 v[104:107], v[152:155], v[176:179], v[104:107]
	v_mfma_f32_16x16x32_bf16 v[100:103], v[160:163], v[176:179], v[100:103]
	v_mfma_f32_16x16x32_bf16 v[88:91], v[152:155], v[184:187], v[88:91]
	v_mfma_f32_16x16x32_bf16 v[84:87], v[160:163], v[184:187], v[84:87]
	v_mfma_f32_16x16x32_bf16 v[72:75], v[152:155], v[204:207], v[72:75]
	v_mfma_f32_16x16x32_bf16 v[68:71], v[160:163], v[204:207], v[68:71]
	s_setprio 0
	s_barrier
	s_add_i32 s22, s58, s28
	v_lshl_add_u64 v[208:209], v[208:209], 0, s[76:77]
	s_mov_b32 m0, s22
	s_nop 0
	global_load_lds_dwordx4 v[208:209], off
	s_add_i32 m0, s22, 0x2000
	s_add_u32 s22, s24, 0x160080
	v_lshl_add_u64 v[208:209], v[210:211], 0, s[76:77]
	s_addc_u32 s23, s25, 0
	s_add_i32 s24, s59, s28
	global_load_lds_dwordx4 v[208:209], off
	v_lshl_add_u64 v[208:209], s[22:23], 0, v[192:193]
	s_mov_b32 m0, s24
	s_nop 0
	global_load_lds_dwordx4 v[208:209], off
	v_lshl_add_u64 v[208:209], s[22:23], 0, v[188:189]
	s_add_i32 m0, s24, 0x2000
	s_nop 0
	global_load_lds_dwordx4 v[208:209], off
	v_lshl_add_u64 v[208:209], v[220:221], 0, s[76:77]
	s_mov_b32 m0, s40
	s_nop 0
	global_load_lds_dwordx4 v[208:209], off
	v_lshl_add_u64 v[208:209], v[222:223], 0, s[76:77]
	s_mov_b32 m0, s41
	s_nop 0
	global_load_lds_dwordx4 v[208:209], off
	ds_read_b128 v[164:167], v217 offset:49152
	ds_read_b128 v[168:171], v217 offset:50176
	ds_read_b128 v[172:175], v217 offset:51200
	ds_read_b128 v[176:179], v217 offset:52224
	ds_read_b128 v[180:183], v217 offset:53248
	ds_read_b128 v[184:187], v217 offset:54272
	ds_read_b128 v[200:203], v217 offset:55296
	ds_read_b128 v[204:207], v217 offset:56320
	s_waitcnt vmcnt(8)
	s_waitcnt lgkmcnt(0)
	s_barrier
	s_setprio 1
	s_waitcnt lgkmcnt(0)
	v_mfma_f32_16x16x32_bf16 v[64:67], v[124:127], v[164:167], v[64:67]
	v_mfma_f32_16x16x32_bf16 v[60:63], v[132:135], v[164:167], v[60:63]
	v_mfma_f32_16x16x32_bf16 v[48:51], v[124:127], v[172:175], v[48:51]
	v_mfma_f32_16x16x32_bf16 v[44:47], v[132:135], v[172:175], v[44:47]
	v_mfma_f32_16x16x32_bf16 v[32:35], v[124:127], v[180:183], v[32:35]
	v_mfma_f32_16x16x32_bf16 v[28:31], v[132:135], v[180:183], v[28:31]
	v_mfma_f32_16x16x32_bf16 v[16:19], v[124:127], v[200:203], v[16:19]
	v_mfma_f32_16x16x32_bf16 v[12:15], v[132:135], v[200:203], v[12:15]
	v_mfma_f32_16x16x32_bf16 v[64:67], v[128:131], v[168:171], v[64:67]
	v_mfma_f32_16x16x32_bf16 v[60:63], v[136:139], v[168:171], v[60:63]
	v_mfma_f32_16x16x32_bf16 v[48:51], v[128:131], v[176:179], v[48:51]
	v_mfma_f32_16x16x32_bf16 v[44:47], v[136:139], v[176:179], v[44:47]
	v_mfma_f32_16x16x32_bf16 v[32:35], v[128:131], v[184:187], v[32:35]
	v_mfma_f32_16x16x32_bf16 v[28:31], v[136:139], v[184:187], v[28:31]
	v_mfma_f32_16x16x32_bf16 v[16:19], v[128:131], v[204:207], v[16:19]
	v_mfma_f32_16x16x32_bf16 v[12:15], v[136:139], v[204:207], v[12:15]
	s_setprio 0
	s_setprio 1
	v_mfma_f32_16x16x32_bf16 v[56:59], v[148:151], v[164:167], v[56:59]
	v_mfma_f32_16x16x32_bf16 v[52:55], v[156:159], v[164:167], v[52:55]
	v_mfma_f32_16x16x32_bf16 v[40:43], v[148:151], v[172:175], v[40:43]
	v_mfma_f32_16x16x32_bf16 v[36:39], v[156:159], v[172:175], v[36:39]
	v_mfma_f32_16x16x32_bf16 v[24:27], v[148:151], v[180:183], v[24:27]
	v_mfma_f32_16x16x32_bf16 v[20:23], v[156:159], v[180:183], v[20:23]
	v_mfma_f32_16x16x32_bf16 v[8:11], v[148:151], v[200:203], v[8:11]
	v_mfma_f32_16x16x32_bf16 v[4:7], v[156:159], v[200:203], v[4:7]
	v_mfma_f32_16x16x32_bf16 v[56:59], v[152:155], v[168:171], v[56:59]
	v_mfma_f32_16x16x32_bf16 v[52:55], v[160:163], v[168:171], v[52:55]
	v_mfma_f32_16x16x32_bf16 v[40:43], v[152:155], v[176:179], v[40:43]
	v_mfma_f32_16x16x32_bf16 v[36:39], v[160:163], v[176:179], v[36:39]
	v_mfma_f32_16x16x32_bf16 v[24:27], v[152:155], v[184:187], v[24:27]
	v_mfma_f32_16x16x32_bf16 v[20:23], v[160:163], v[184:187], v[20:23]
	v_mfma_f32_16x16x32_bf16 v[8:11], v[152:155], v[204:207], v[8:11]
	v_mfma_f32_16x16x32_bf16 v[4:7], v[160:163], v[204:207], v[4:7]
	s_setprio 0
	s_barrier
	s_add_i32 s57, s57, 2
	s_add_u32 s52, s52, 0x100
	s_addc_u32 s56, s56, 0
	s_cmpk_gt_u32 s57, 0x55
	s_mov_b64 s[22:23], s[4:5]
	s_cbranch_scc0 .LBB0_1504
	s_and_b64 vcc, exec, s[16:17]
	s_cbranch_vccz .LBB0_1507
	s_barrier
